# v13 with the select loop specialised in steps of 8 key registers (7 copies) instead of 16
# speedup vs baseline: 1.0141x; 1.0054x over previous
; __device__ __forceinline__ void select_item(const Frame& F, int l, int samp, int b, int c, int qg) {
;     int tid = F.tid, lane = F.lane; const int wave = F.wave; asm volatile("" : "+v"(tid), "+v"(lane));
;     __attribute__((address_space(1))) unsigned char* wsl_ = (__attribute__((address_space(1))) unsigned char*)F.ws; asm volatile("" : "+s"(wsl_)); unsigned char* ws = (unsigned char*)wsl_;
;     const int r0 = samp ? MP + b * 64 : b * SEQ + c * 64;
;     const int L = samp ? SKS : 64 * (c + 1);
;     const int nj = L >> 6;
;     u64* SEL = (u64*)(ws + WS_SEL) + (size_t)r0 * 64;
;     const int qA = qg * 16 + wave * 2, qB = qA + 1;
;     u64 mywA = 0ull, mywB = 0ull;
;     if (L <= 256) { mywA = (lane < nj) ? ~0ull : 0ull; mywB = mywA; }
;     else {
;         {
;             unsigned* cw = F.ctl + CW_SCD + 16 * (l * 160 + sel_uid(samp, b, c)); const unsigned need = (unsigned)sel_nchunks(samp, c);
.LBB0_1298:
	s_and_b64 vcc, exec, s[0:1]
	s_cbranch_vccz .LBB0_1458
	s_bfe_u32 s9, s33, 0x60002
	s_ashr_i32 s4, s33, 8
	s_xor_b32 s6, s9, 63
	s_lshr_b32 s98, s6, 3
	s_lshl_b32 s0, s4, 12
	s_lshl_b32 s1, s6, 6
	s_or_b32 s14, s1, s0
	s_lshl_b32 s0, s74, 4
	v_mov_b32_e32 v0, v198
	s_add_i32 s12, s0, s86
	v_mov_b32_e32 v1, v199
	s_mov_b64 s[10:11], s[90:91]
	s_cmp_gt_u32 s6, 3
	s_mov_b64 s[0:1], -1
	s_cbranch_scc0 .LBB0_1455
	s_lshl_b32 s0, s4, 6
	v_readlane_b32 s1, v254, 38
	s_add_i32 s0, s0, s1
	s_add_i32 s0, s0, s6
	s_lshl_b32 s0, s0, 4
	s_ashr_i32 s1, s0, 31
	s_lshl_b64 s[0:1], s[0:1], 2
	v_readlane_b32 s4, v254, 31
	s_add_u32 s0, s4, s0
	v_readlane_b32 s4, v254, 37
	s_addc_u32 s1, s4, s1
	s_sub_i32 s4, 0x47, s9
	s_lshr_b32 s7, s4, 3
	s_mov_b32 s8, 0x400001
	s_branch .LBB0_1302

; __device__ __forceinline__ void select_item(const Frame& F, int l, int samp, int b, int c, int qg) {
;     ...
;             const unsigned candA = prefixA | (1u << bit), candB = prefixB | (1u << bit), cA1 = candA - 1u, cB1 = candB - 1u; unsigned a4[4] = {0u, 0u, 0u, 0u}, b4[4] = {0u, 0u, 0u, 0u};
; #pragma unroll
;             for (int j = 0; j < 64; ++j) { a4[j & 3] += min(__builtin_elementwise_sub_sat(keyA[j], cA1), 1u); b4[j & 3] += min(__builtin_elementwise_sub_sat(keyB[j], cB1), 1u); }
;             const int cntA = wave_sum_i_dpp((int)((a4[0] + a4[1]) + (a4[2] + a4[3]))), cntB = wave_sum_i_dpp((int)((b4[0] + b4[1]) + (b4[2] + b4[3])));
;             if (!doneA) { if (cntA >= 256) prefixA = candA; if (cntA == 256) doneA = true; }
;             if (!doneB) { if (cntB >= 256) prefixB = candB; if (cntB == 256) doneB = true; }
;         }
.Lsel_m1:
	s_mov_b64 s[6:7], s[0:1]
	s_lshl_b32 s0, 1, s11
	s_or_b32 s13, s0, s10
	s_or_b32 s12, s0, s33
	s_add_i32 s14, s13, -1
	s_add_i32 s15, s12, -1
	v_sub_co_u32_e64 v2, s[8:9], s11, 1
	s_nop 0
	v_readfirstlane_b32 s11, v2
	s_mov_b64 s[4:5], s[42:43]
	s_cmp_lt_u32 s14, 0x7fffff
	s_cselect_b32 s0, 56, 0
	v_mov_b32_e32 v2, s0
	s_cmp_lt_u32 s15, 0x7fffff
	s_cselect_b32 s0, 56, 0
	v_mov_b32_e32 v3, s0
	v_cmp_lt_u32_e64 s[0:1], s14, v127
	v_cmp_lt_u32_e64 s[100:101], s15, v81
	v_cmp_lt_u32_e32 vcc, s14, v4
	v_cndmask_b32_e64 v132, 0, 1, s[0:1]
	v_cndmask_b32_e64 v133, 0, 1, s[100:101]
	v_addc_co_u32_e32 v2, vcc, v2, v132, vcc
	v_cmp_lt_u32_e32 vcc, s15, v6
	v_cmp_lt_u32_e64 s[0:1], s14, v65
	v_cmp_lt_u32_e64 s[100:101], s15, v7
	v_addc_co_u32_e32 v3, vcc, v3, v133, vcc
	v_cmp_lt_u32_e32 vcc, s14, v129
	v_cndmask_b32_e64 v132, 0, 1, s[0:1]
	v_cndmask_b32_e64 v133, 0, 1, s[100:101]
	v_addc_co_u32_e32 v2, vcc, v2, v132, vcc
	v_cmp_lt_u32_e32 vcc, s15, v8
	v_cmp_lt_u32_e64 s[0:1], s14, v67
	v_cmp_lt_u32_e64 s[100:101], s15, v83
	v_addc_co_u32_e32 v3, vcc, v3, v133, vcc
	v_cmp_lt_u32_e32 vcc, s14, v128
	v_cndmask_b32_e64 v132, 0, 1, s[0:1]
	v_cndmask_b32_e64 v133, 0, 1, s[100:101]
	v_addc_co_u32_e32 v2, vcc, v2, v132, vcc
	v_cmp_lt_u32_e32 vcc, s15, v82
	v_cmp_lt_u32_e64 s[0:1], s14, v131
	v_cmp_lt_u32_e64 s[100:101], s15, v85
	v_addc_co_u32_e32 v3, vcc, v3, v133, vcc
	v_cmp_lt_u32_e32 vcc, s14, v130
	v_cndmask_b32_e64 v132, 0, 1, s[0:1]
	v_cndmask_b32_e64 v133, 0, 1, s[100:101]
	v_addc_co_u32_e32 v2, vcc, v2, v132, vcc
	v_cmp_lt_u32_e32 vcc, s15, v84
	s_nop 1
	v_addc_co_u32_e32 v3, vcc, v3, v133, vcc
	s_nop 1
	v_add_u32_dpp v2, v2, v2 quad_perm:[1,0,3,2] row_mask:0xf bank_mask:0xf bound_ctrl:1
	v_add_u32_dpp v3, v3, v3 quad_perm:[1,0,3,2] row_mask:0xf bank_mask:0xf bound_ctrl:1
	s_nop 0
	v_add_u32_dpp v2, v2, v2 quad_perm:[2,3,0,1] row_mask:0xf bank_mask:0xf bound_ctrl:1
	v_add_u32_dpp v3, v3, v3 quad_perm:[2,3,0,1] row_mask:0xf bank_mask:0xf bound_ctrl:1
	s_nop 0
	v_add_u32_dpp v2, v2, v2 row_half_mirror row_mask:0xf bank_mask:0xf bound_ctrl:1
	v_add_u32_dpp v3, v3, v3 row_half_mirror row_mask:0xf bank_mask:0xf bound_ctrl:1
	s_nop 0
	v_add_u32_dpp v2, v2, v2 row_mirror row_mask:0xf bank_mask:0xf bound_ctrl:1
	v_add_u32_dpp v3, v3, v3 row_mirror row_mask:0xf bank_mask:0xf bound_ctrl:1
	s_nop 0
	v_add_u32_dpp v2, v2, v2 row_bcast:15 row_mask:0xa bank_mask:0xf
	v_add_u32_dpp v3, v3, v3 row_bcast:15 row_mask:0xa bank_mask:0xf
	s_nop 0
	v_add_u32_dpp v2, v2, v2 row_bcast:31 row_mask:0xc bank_mask:0xf
	v_add_u32_dpp v3, v3, v3 row_bcast:31 row_mask:0xc bank_mask:0xf
	v_readlane_b32 s0, v2, 63
	s_cmpk_gt_i32 s0, 0xff
	s_cselect_b32 s13, s13, s10
	s_cmpk_eq_i32 s0, 0x100
	s_cselect_b64 s[0:1], -1, 0
	s_or_b64 s[0:1], s[6:7], s[0:1]
	s_and_b64 s[6:7], s[6:7], exec
	s_cselect_b32 s10, s10, s13
	v_readlane_b32 s14, v3, 63
	s_cmpk_gt_i32 s14, 0xff
	s_cselect_b32 s12, s12, s33
	s_cmpk_eq_i32 s14, 0x100
	s_cselect_b64 s[6:7], -1, 0
	s_or_b64 s[42:43], s[42:43], s[6:7]
	s_and_b64 s[4:5], s[4:5], exec
	s_cselect_b32 s33, s33, s12
	s_and_b64 s[4:5], s[0:1], s[42:43]
	s_or_b64 s[4:5], s[8:9], s[4:5]
	s_and_b64 vcc, exec, s[4:5]
	s_cbranch_vccz .Lsel_m1
	s_branch .Lsel_exit

; __device__ __forceinline__ void select_item(const Frame& F, int l, int samp, int b, int c, int qg) {
;     ...
;             const unsigned candA = prefixA | (1u << bit), candB = prefixB | (1u << bit), cA1 = candA - 1u, cB1 = candB - 1u; unsigned a4[4] = {0u, 0u, 0u, 0u}, b4[4] = {0u, 0u, 0u, 0u};
; #pragma unroll
;             for (int j = 0; j < 64; ++j) { a4[j & 3] += min(__builtin_elementwise_sub_sat(keyA[j], cA1), 1u); b4[j & 3] += min(__builtin_elementwise_sub_sat(keyB[j], cB1), 1u); }
;             const int cntA = wave_sum_i_dpp((int)((a4[0] + a4[1]) + (a4[2] + a4[3]))), cntB = wave_sum_i_dpp((int)((b4[0] + b4[1]) + (b4[2] + b4[3])));
;             if (!doneA) { if (cntA >= 256) prefixA = candA; if (cntA == 256) doneA = true; }
;             if (!doneB) { if (cntB >= 256) prefixB = candB; if (cntB == 256) doneB = true; }
;         }
.Lsel_m3:
	s_mov_b64 s[6:7], s[0:1]
	s_lshl_b32 s0, 1, s11
	s_or_b32 s13, s0, s10
	s_or_b32 s12, s0, s33
	s_add_i32 s14, s13, -1
	s_add_i32 s15, s12, -1
	v_sub_co_u32_e64 v2, s[8:9], s11, 1
	s_nop 0
	v_readfirstlane_b32 s11, v2
	s_mov_b64 s[4:5], s[42:43]
	s_cmp_lt_u32 s14, 0x7fffff
	s_cselect_b32 s0, 40, 0
	v_mov_b32_e32 v2, s0
	s_cmp_lt_u32 s15, 0x7fffff
	s_cselect_b32 s0, 40, 0
	v_mov_b32_e32 v3, s0
	v_cmp_lt_u32_e64 s[0:1], s14, v127
	v_cmp_lt_u32_e64 s[100:101], s15, v81
	v_cmp_lt_u32_e32 vcc, s14, v4
	v_cndmask_b32_e64 v132, 0, 1, s[0:1]
	v_cndmask_b32_e64 v133, 0, 1, s[100:101]
	v_addc_co_u32_e32 v2, vcc, v2, v132, vcc
	v_cmp_lt_u32_e32 vcc, s15, v6
	v_cmp_lt_u32_e64 s[0:1], s14, v65
	v_cmp_lt_u32_e64 s[100:101], s15, v7
	v_addc_co_u32_e32 v3, vcc, v3, v133, vcc
	v_cmp_lt_u32_e32 vcc, s14, v129
	v_cndmask_b32_e64 v132, 0, 1, s[0:1]
	v_cndmask_b32_e64 v133, 0, 1, s[100:101]
	v_addc_co_u32_e32 v2, vcc, v2, v132, vcc
	v_cmp_lt_u32_e32 vcc, s15, v8
	v_cmp_lt_u32_e64 s[0:1], s14, v70
	v_cmp_lt_u32_e64 s[100:101], s15, v9
	v_addc_co_u32_e32 v3, vcc, v3, v133, vcc
	v_cmp_lt_u32_e32 vcc, s14, v67
	v_cndmask_b32_e64 v132, 0, 1, s[0:1]
	v_cndmask_b32_e64 v133, 0, 1, s[100:101]
	v_addc_co_u32_e32 v2, vcc, v2, v132, vcc
	v_cmp_lt_u32_e32 vcc, s15, v10
	v_cmp_lt_u32_e64 s[0:1], s14, v5
	v_cmp_lt_u32_e64 s[100:101], s15, v11
	v_addc_co_u32_e32 v3, vcc, v3, v133, vcc
	v_cmp_lt_u32_e32 vcc, s14, v69
	v_cndmask_b32_e64 v132, 0, 1, s[0:1]
	v_cndmask_b32_e64 v133, 0, 1, s[100:101]
	v_addc_co_u32_e32 v2, vcc, v2, v132, vcc
	v_cmp_lt_u32_e32 vcc, s15, v12
	v_cmp_lt_u32_e64 s[0:1], s14, v66
	v_cmp_lt_u32_e64 s[100:101], s15, v17
	v_addc_co_u32_e32 v3, vcc, v3, v133, vcc
	v_cmp_lt_u32_e32 vcc, s14, v71
	v_cndmask_b32_e64 v132, 0, 1, s[0:1]
	v_cndmask_b32_e64 v133, 0, 1, s[100:101]
	v_addc_co_u32_e32 v2, vcc, v2, v132, vcc
	v_cmp_lt_u32_e32 vcc, s15, v18
	v_cmp_lt_u32_e64 s[0:1], s14, v79
	v_cmp_lt_u32_e64 s[100:101], s15, v19
	v_addc_co_u32_e32 v3, vcc, v3, v133, vcc
	v_cmp_lt_u32_e32 vcc, s14, v72
	v_cndmask_b32_e64 v132, 0, 1, s[0:1]
	v_cndmask_b32_e64 v133, 0, 1, s[100:101]
	v_addc_co_u32_e32 v2, vcc, v2, v132, vcc
	v_cmp_lt_u32_e32 vcc, s15, v20
	v_cmp_lt_u32_e64 s[0:1], s14, v76
	v_cmp_lt_u32_e64 s[100:101], s15, v83
	v_addc_co_u32_e32 v3, vcc, v3, v133, vcc
	v_cmp_lt_u32_e32 vcc, s14, v74
	v_cndmask_b32_e64 v132, 0, 1, s[0:1]
	v_cndmask_b32_e64 v133, 0, 1, s[100:101]
	v_addc_co_u32_e32 v2, vcc, v2, v132, vcc
	v_cmp_lt_u32_e32 vcc, s15, v15
	v_cmp_lt_u32_e64 s[0:1], s14, v78
	v_cmp_lt_u32_e64 s[100:101], s15, v23
	v_addc_co_u32_e32 v3, vcc, v3, v133, vcc
	v_cmp_lt_u32_e32 vcc, s14, v128
	v_cndmask_b32_e64 v132, 0, 1, s[0:1]
	v_cndmask_b32_e64 v133, 0, 1, s[100:101]
	v_addc_co_u32_e32 v2, vcc, v2, v132, vcc
	v_cmp_lt_u32_e32 vcc, s15, v82
	v_cmp_lt_u32_e64 s[0:1], s14, v75
	v_cmp_lt_u32_e64 s[100:101], s15, v16
	v_addc_co_u32_e32 v3, vcc, v3, v133, vcc
	v_cmp_lt_u32_e32 vcc, s14, v87
	v_cndmask_b32_e64 v132, 0, 1, s[0:1]
	v_cndmask_b32_e64 v133, 0, 1, s[100:101]
	v_addc_co_u32_e32 v2, vcc, v2, v132, vcc
	v_cmp_lt_u32_e32 vcc, s15, v24
	v_cmp_lt_u32_e64 s[0:1], s14, v131
	v_cmp_lt_u32_e64 s[100:101], s15, v85
	v_addc_co_u32_e32 v3, vcc, v3, v133, vcc
	v_cmp_lt_u32_e32 vcc, s14, v68
	v_cndmask_b32_e64 v132, 0, 1, s[0:1]
	v_cndmask_b32_e64 v133, 0, 1, s[100:101]
	v_addc_co_u32_e32 v2, vcc, v2, v132, vcc
	v_cmp_lt_u32_e32 vcc, s15, v13
	v_cmp_lt_u32_e64 s[0:1], s14, v77
	v_cmp_lt_u32_e64 s[100:101], s15, v21
	v_addc_co_u32_e32 v3, vcc, v3, v133, vcc
	v_cmp_lt_u32_e32 vcc, s14, v130
	v_cndmask_b32_e64 v132, 0, 1, s[0:1]
	v_cndmask_b32_e64 v133, 0, 1, s[100:101]
	v_addc_co_u32_e32 v2, vcc, v2, v132, vcc
	v_cmp_lt_u32_e32 vcc, s15, v84
	v_cmp_lt_u32_e64 s[0:1], s14, v73
	v_cmp_lt_u32_e64 s[100:101], s15, v14
	v_addc_co_u32_e32 v3, vcc, v3, v133, vcc
	v_cmp_lt_u32_e32 vcc, s14, v80
	v_cndmask_b32_e64 v132, 0, 1, s[0:1]
	v_cndmask_b32_e64 v133, 0, 1, s[100:101]
	v_addc_co_u32_e32 v2, vcc, v2, v132, vcc
	v_cmp_lt_u32_e32 vcc, s15, v22
	s_nop 1
	v_addc_co_u32_e32 v3, vcc, v3, v133, vcc
	s_nop 1
	v_add_u32_dpp v2, v2, v2 quad_perm:[1,0,3,2] row_mask:0xf bank_mask:0xf bound_ctrl:1
	v_add_u32_dpp v3, v3, v3 quad_perm:[1,0,3,2] row_mask:0xf bank_mask:0xf bound_ctrl:1
	s_nop 0
	v_add_u32_dpp v2, v2, v2 quad_perm:[2,3,0,1] row_mask:0xf bank_mask:0xf bound_ctrl:1
	v_add_u32_dpp v3, v3, v3 quad_perm:[2,3,0,1] row_mask:0xf bank_mask:0xf bound_ctrl:1
	s_nop 0
	v_add_u32_dpp v2, v2, v2 row_half_mirror row_mask:0xf bank_mask:0xf bound_ctrl:1
	v_add_u32_dpp v3, v3, v3 row_half_mirror row_mask:0xf bank_mask:0xf bound_ctrl:1
	s_nop 0
	v_add_u32_dpp v2, v2, v2 row_mirror row_mask:0xf bank_mask:0xf bound_ctrl:1
	v_add_u32_dpp v3, v3, v3 row_mirror row_mask:0xf bank_mask:0xf bound_ctrl:1
	s_nop 0
	v_add_u32_dpp v2, v2, v2 row_bcast:15 row_mask:0xa bank_mask:0xf
	v_add_u32_dpp v3, v3, v3 row_bcast:15 row_mask:0xa bank_mask:0xf
	s_nop 0
	v_add_u32_dpp v2, v2, v2 row_bcast:31 row_mask:0xc bank_mask:0xf
	v_add_u32_dpp v3, v3, v3 row_bcast:31 row_mask:0xc bank_mask:0xf
	v_readlane_b32 s0, v2, 63
	s_cmpk_gt_i32 s0, 0xff
	s_cselect_b32 s13, s13, s10
	s_cmpk_eq_i32 s0, 0x100
	s_cselect_b64 s[0:1], -1, 0
	s_or_b64 s[0:1], s[6:7], s[0:1]
	s_and_b64 s[6:7], s[6:7], exec
	s_cselect_b32 s10, s10, s13
	v_readlane_b32 s14, v3, 63
	s_cmpk_gt_i32 s14, 0xff
	s_cselect_b32 s12, s12, s33
	s_cmpk_eq_i32 s14, 0x100
	s_cselect_b64 s[6:7], -1, 0
	s_or_b64 s[42:43], s[42:43], s[6:7]
	s_and_b64 s[4:5], s[4:5], exec
	s_cselect_b32 s33, s33, s12
	s_and_b64 s[4:5], s[0:1], s[42:43]
	s_or_b64 s[4:5], s[8:9], s[4:5]
	s_and_b64 vcc, exec, s[4:5]
	s_cbranch_vccz .Lsel_m3
	s_branch .Lsel_exit

; __device__ __forceinline__ void select_item(const Frame& F, int l, int samp, int b, int c, int qg) {
;     ...
;             const unsigned candA = prefixA | (1u << bit), candB = prefixB | (1u << bit), cA1 = candA - 1u, cB1 = candB - 1u; unsigned a4[4] = {0u, 0u, 0u, 0u}, b4[4] = {0u, 0u, 0u, 0u};
; #pragma unroll
;             for (int j = 0; j < 64; ++j) { a4[j & 3] += min(__builtin_elementwise_sub_sat(keyA[j], cA1), 1u); b4[j & 3] += min(__builtin_elementwise_sub_sat(keyB[j], cB1), 1u); }
;             const int cntA = wave_sum_i_dpp((int)((a4[0] + a4[1]) + (a4[2] + a4[3]))), cntB = wave_sum_i_dpp((int)((b4[0] + b4[1]) + (b4[2] + b4[3])));
;             if (!doneA) { if (cntA >= 256) prefixA = candA; if (cntA == 256) doneA = true; }
;             if (!doneB) { if (cntB >= 256) prefixB = candB; if (cntB == 256) doneB = true; }
;         }
.Lsel_m5:
	s_mov_b64 s[6:7], s[0:1]
	s_lshl_b32 s0, 1, s11
	s_or_b32 s13, s0, s10
	s_or_b32 s12, s0, s33
	s_add_i32 s14, s13, -1
	s_add_i32 s15, s12, -1
	v_sub_co_u32_e64 v2, s[8:9], s11, 1
	s_nop 0
	v_readfirstlane_b32 s11, v2
	s_mov_b64 s[4:5], s[42:43]
	s_cmp_lt_u32 s14, 0x7fffff
	s_cselect_b32 s0, 24, 0
	v_mov_b32_e32 v2, s0
	s_cmp_lt_u32 s15, 0x7fffff
	s_cselect_b32 s0, 24, 0
	v_mov_b32_e32 v3, s0
	v_cmp_lt_u32_e64 s[0:1], s14, v127
	v_cmp_lt_u32_e64 s[100:101], s15, v81
	v_cmp_lt_u32_e32 vcc, s14, v4
	v_cndmask_b32_e64 v132, 0, 1, s[0:1]
	v_cndmask_b32_e64 v133, 0, 1, s[100:101]
	v_addc_co_u32_e32 v2, vcc, v2, v132, vcc
	v_cmp_lt_u32_e32 vcc, s15, v6
	v_cmp_lt_u32_e64 s[0:1], s14, v65
	v_cmp_lt_u32_e64 s[100:101], s15, v7
	v_addc_co_u32_e32 v3, vcc, v3, v133, vcc
	v_cmp_lt_u32_e32 vcc, s14, v129
	v_cndmask_b32_e64 v132, 0, 1, s[0:1]
	v_cndmask_b32_e64 v133, 0, 1, s[100:101]
	v_addc_co_u32_e32 v2, vcc, v2, v132, vcc
	v_cmp_lt_u32_e32 vcc, s15, v8
	v_cmp_lt_u32_e64 s[0:1], s14, v70
	v_cmp_lt_u32_e64 s[100:101], s15, v9
	v_addc_co_u32_e32 v3, vcc, v3, v133, vcc
	v_cmp_lt_u32_e32 vcc, s14, v67
	v_cndmask_b32_e64 v132, 0, 1, s[0:1]
	v_cndmask_b32_e64 v133, 0, 1, s[100:101]
	v_addc_co_u32_e32 v2, vcc, v2, v132, vcc
	v_cmp_lt_u32_e32 vcc, s15, v10
	v_cmp_lt_u32_e64 s[0:1], s14, v5
	v_cmp_lt_u32_e64 s[100:101], s15, v11
	v_addc_co_u32_e32 v3, vcc, v3, v133, vcc
	v_cmp_lt_u32_e32 vcc, s14, v69
	v_cndmask_b32_e64 v132, 0, 1, s[0:1]
	v_cndmask_b32_e64 v133, 0, 1, s[100:101]
	v_addc_co_u32_e32 v2, vcc, v2, v132, vcc
	v_cmp_lt_u32_e32 vcc, s15, v12
	v_cmp_lt_u32_e64 s[0:1], s14, v66
	v_cmp_lt_u32_e64 s[100:101], s15, v17
	v_addc_co_u32_e32 v3, vcc, v3, v133, vcc
	v_cmp_lt_u32_e32 vcc, s14, v71
	v_cndmask_b32_e64 v132, 0, 1, s[0:1]
	v_cndmask_b32_e64 v133, 0, 1, s[100:101]
	v_addc_co_u32_e32 v2, vcc, v2, v132, vcc
	v_cmp_lt_u32_e32 vcc, s15, v18
	v_cmp_lt_u32_e64 s[0:1], s14, v79
	v_cmp_lt_u32_e64 s[100:101], s15, v19
	v_addc_co_u32_e32 v3, vcc, v3, v133, vcc
	v_cmp_lt_u32_e32 vcc, s14, v72
	v_cndmask_b32_e64 v132, 0, 1, s[0:1]
	v_cndmask_b32_e64 v133, 0, 1, s[100:101]
	v_addc_co_u32_e32 v2, vcc, v2, v132, vcc
	v_cmp_lt_u32_e32 vcc, s15, v20
	v_cmp_lt_u32_e64 s[0:1], s14, v76
	v_cmp_lt_u32_e64 s[100:101], s15, v25
	v_addc_co_u32_e32 v3, vcc, v3, v133, vcc
	v_cmp_lt_u32_e32 vcc, s14, v74
	v_cndmask_b32_e64 v132, 0, 1, s[0:1]
	v_cndmask_b32_e64 v133, 0, 1, s[100:101]
	v_addc_co_u32_e32 v2, vcc, v2, v132, vcc
	v_cmp_lt_u32_e32 vcc, s15, v26
	v_cmp_lt_u32_e64 s[0:1], s14, v78
	v_cmp_lt_u32_e64 s[100:101], s15, v27
	v_addc_co_u32_e32 v3, vcc, v3, v133, vcc
	v_cmp_lt_u32_e32 vcc, s14, v92
	v_cndmask_b32_e64 v132, 0, 1, s[0:1]
	v_cndmask_b32_e64 v133, 0, 1, s[100:101]
	v_addc_co_u32_e32 v2, vcc, v2, v132, vcc
	v_cmp_lt_u32_e32 vcc, s15, v28
	v_cmp_lt_u32_e64 s[0:1], s14, v86
	v_cmp_lt_u32_e64 s[100:101], s15, v33
	v_addc_co_u32_e32 v3, vcc, v3, v133, vcc
	v_cmp_lt_u32_e32 vcc, s14, v89
	v_cndmask_b32_e64 v132, 0, 1, s[0:1]
	v_cndmask_b32_e64 v133, 0, 1, s[100:101]
	v_addc_co_u32_e32 v2, vcc, v2, v132, vcc
	v_cmp_lt_u32_e32 vcc, s15, v34
	v_cmp_lt_u32_e64 s[0:1], s14, v88
	v_cmp_lt_u32_e64 s[100:101], s15, v35
	v_addc_co_u32_e32 v3, vcc, v3, v133, vcc
	v_cmp_lt_u32_e32 vcc, s14, v91
	v_cndmask_b32_e64 v132, 0, 1, s[0:1]
	v_cndmask_b32_e64 v133, 0, 1, s[100:101]
	v_addc_co_u32_e32 v2, vcc, v2, v132, vcc
	v_cmp_lt_u32_e32 vcc, s15, v36
	v_cmp_lt_u32_e64 s[0:1], s14, v100
	v_cmp_lt_u32_e64 s[100:101], s15, v83
	v_addc_co_u32_e32 v3, vcc, v3, v133, vcc
	v_cmp_lt_u32_e32 vcc, s14, v94
	v_cndmask_b32_e64 v132, 0, 1, s[0:1]
	v_cndmask_b32_e64 v133, 0, 1, s[100:101]
	v_addc_co_u32_e32 v2, vcc, v2, v132, vcc
	v_cmp_lt_u32_e32 vcc, s15, v15
	v_cmp_lt_u32_e64 s[0:1], s14, v97
	v_cmp_lt_u32_e64 s[100:101], s15, v23
	v_addc_co_u32_e32 v3, vcc, v3, v133, vcc
	v_cmp_lt_u32_e32 vcc, s14, v96
	v_cndmask_b32_e64 v132, 0, 1, s[0:1]
	v_cndmask_b32_e64 v133, 0, 1, s[100:101]
	v_addc_co_u32_e32 v2, vcc, v2, v132, vcc
	v_cmp_lt_u32_e32 vcc, s15, v31
	v_cmp_lt_u32_e64 s[0:1], s14, v99
; __device__ __forceinline__ void select_item(const Frame& F, int l, int samp, int b, int c, int qg) {
;     ...
;             const unsigned candA = prefixA | (1u << bit), candB = prefixB | (1u << bit), cA1 = candA - 1u, cB1 = candB - 1u; unsigned a4[4] = {0u, 0u, 0u, 0u}, b4[4] = {0u, 0u, 0u, 0u};
; #pragma unroll
;             for (int j = 0; j < 64; ++j) { a4[j & 3] += min(__builtin_elementwise_sub_sat(keyA[j], cA1), 1u); b4[j & 3] += min(__builtin_elementwise_sub_sat(keyB[j], cB1), 1u); }
;             const int cntA = wave_sum_i_dpp((int)((a4[0] + a4[1]) + (a4[2] + a4[3]))), cntB = wave_sum_i_dpp((int)((b4[0] + b4[1]) + (b4[2] + b4[3])));
;             if (!doneA) { if (cntA >= 256) prefixA = candA; if (cntA == 256) doneA = true; }
;             if (!doneB) { if (cntB >= 256) prefixB = candB; if (cntB == 256) doneB = true; }
;         }
	v_cmp_lt_u32_e64 s[100:101], s15, v39
	v_addc_co_u32_e32 v3, vcc, v3, v133, vcc
	v_cmp_lt_u32_e32 vcc, s14, v128
	v_cndmask_b32_e64 v132, 0, 1, s[0:1]
	v_cndmask_b32_e64 v133, 0, 1, s[100:101]
	v_addc_co_u32_e32 v2, vcc, v2, v132, vcc
	v_cmp_lt_u32_e32 vcc, s15, v82
	v_cmp_lt_u32_e64 s[0:1], s14, v75
	v_cmp_lt_u32_e64 s[100:101], s15, v16
	v_addc_co_u32_e32 v3, vcc, v3, v133, vcc
	v_cmp_lt_u32_e32 vcc, s14, v87
	v_cndmask_b32_e64 v132, 0, 1, s[0:1]
	v_cndmask_b32_e64 v133, 0, 1, s[100:101]
	v_addc_co_u32_e32 v2, vcc, v2, v132, vcc
	v_cmp_lt_u32_e32 vcc, s15, v24
	v_cmp_lt_u32_e64 s[0:1], s14, v95
	v_cmp_lt_u32_e64 s[100:101], s15, v32
	v_addc_co_u32_e32 v3, vcc, v3, v133, vcc
	v_cmp_lt_u32_e32 vcc, s14, v103
	v_cndmask_b32_e64 v132, 0, 1, s[0:1]
	v_cndmask_b32_e64 v133, 0, 1, s[100:101]
	v_addc_co_u32_e32 v2, vcc, v2, v132, vcc
	v_cmp_lt_u32_e32 vcc, s15, v40
	v_cmp_lt_u32_e64 s[0:1], s14, v131
	v_cmp_lt_u32_e64 s[100:101], s15, v85
	v_addc_co_u32_e32 v3, vcc, v3, v133, vcc
	v_cmp_lt_u32_e32 vcc, s14, v68
	v_cndmask_b32_e64 v132, 0, 1, s[0:1]
	v_cndmask_b32_e64 v133, 0, 1, s[100:101]
	v_addc_co_u32_e32 v2, vcc, v2, v132, vcc
	v_cmp_lt_u32_e32 vcc, s15, v13
	v_cmp_lt_u32_e64 s[0:1], s14, v77
	v_cmp_lt_u32_e64 s[100:101], s15, v21
	v_addc_co_u32_e32 v3, vcc, v3, v133, vcc
	v_cmp_lt_u32_e32 vcc, s14, v90
	v_cndmask_b32_e64 v132, 0, 1, s[0:1]
	v_cndmask_b32_e64 v133, 0, 1, s[100:101]
	v_addc_co_u32_e32 v2, vcc, v2, v132, vcc
	v_cmp_lt_u32_e32 vcc, s15, v29
	v_cmp_lt_u32_e64 s[0:1], s14, v98
	v_cmp_lt_u32_e64 s[100:101], s15, v37
	v_addc_co_u32_e32 v3, vcc, v3, v133, vcc
	v_cmp_lt_u32_e32 vcc, s14, v130
	v_cndmask_b32_e64 v132, 0, 1, s[0:1]
	v_cndmask_b32_e64 v133, 0, 1, s[100:101]
	v_addc_co_u32_e32 v2, vcc, v2, v132, vcc
	v_cmp_lt_u32_e32 vcc, s15, v84
	v_cmp_lt_u32_e64 s[0:1], s14, v73
	v_cmp_lt_u32_e64 s[100:101], s15, v14
	v_addc_co_u32_e32 v3, vcc, v3, v133, vcc
	v_cmp_lt_u32_e32 vcc, s14, v80
	v_cndmask_b32_e64 v132, 0, 1, s[0:1]
	v_cndmask_b32_e64 v133, 0, 1, s[100:101]
	v_addc_co_u32_e32 v2, vcc, v2, v132, vcc
	v_cmp_lt_u32_e32 vcc, s15, v22
	v_cmp_lt_u32_e64 s[0:1], s14, v93
	v_cmp_lt_u32_e64 s[100:101], s15, v30
	v_addc_co_u32_e32 v3, vcc, v3, v133, vcc
	v_cmp_lt_u32_e32 vcc, s14, v101
	v_cndmask_b32_e64 v132, 0, 1, s[0:1]
	v_cndmask_b32_e64 v133, 0, 1, s[100:101]
	v_addc_co_u32_e32 v2, vcc, v2, v132, vcc
	v_cmp_lt_u32_e32 vcc, s15, v38
	s_nop 1
	v_addc_co_u32_e32 v3, vcc, v3, v133, vcc
	s_nop 1
	v_add_u32_dpp v2, v2, v2 quad_perm:[1,0,3,2] row_mask:0xf bank_mask:0xf bound_ctrl:1
	v_add_u32_dpp v3, v3, v3 quad_perm:[1,0,3,2] row_mask:0xf bank_mask:0xf bound_ctrl:1
	s_nop 0
	v_add_u32_dpp v2, v2, v2 quad_perm:[2,3,0,1] row_mask:0xf bank_mask:0xf bound_ctrl:1
	v_add_u32_dpp v3, v3, v3 quad_perm:[2,3,0,1] row_mask:0xf bank_mask:0xf bound_ctrl:1
	s_nop 0
	v_add_u32_dpp v2, v2, v2 row_half_mirror row_mask:0xf bank_mask:0xf bound_ctrl:1
	v_add_u32_dpp v3, v3, v3 row_half_mirror row_mask:0xf bank_mask:0xf bound_ctrl:1
	s_nop 0
	v_add_u32_dpp v2, v2, v2 row_mirror row_mask:0xf bank_mask:0xf bound_ctrl:1
	v_add_u32_dpp v3, v3, v3 row_mirror row_mask:0xf bank_mask:0xf bound_ctrl:1
	s_nop 0
	v_add_u32_dpp v2, v2, v2 row_bcast:15 row_mask:0xa bank_mask:0xf
	v_add_u32_dpp v3, v3, v3 row_bcast:15 row_mask:0xa bank_mask:0xf
	s_nop 0
	v_add_u32_dpp v2, v2, v2 row_bcast:31 row_mask:0xc bank_mask:0xf
	v_add_u32_dpp v3, v3, v3 row_bcast:31 row_mask:0xc bank_mask:0xf
	v_readlane_b32 s0, v2, 63
	s_cmpk_gt_i32 s0, 0xff
	s_cselect_b32 s13, s13, s10
	s_cmpk_eq_i32 s0, 0x100
	s_cselect_b64 s[0:1], -1, 0
	s_or_b64 s[0:1], s[6:7], s[0:1]
	s_and_b64 s[6:7], s[6:7], exec
	s_cselect_b32 s10, s10, s13
	v_readlane_b32 s14, v3, 63
	s_cmpk_gt_i32 s14, 0xff
	s_cselect_b32 s12, s12, s33
	s_cmpk_eq_i32 s14, 0x100
	s_cselect_b64 s[6:7], -1, 0
	s_or_b64 s[42:43], s[42:43], s[6:7]
	s_and_b64 s[4:5], s[4:5], exec
	s_cselect_b32 s33, s33, s12
	s_and_b64 s[4:5], s[0:1], s[42:43]
	s_or_b64 s[4:5], s[8:9], s[4:5]
	s_and_b64 vcc, exec, s[4:5]
	s_cbranch_vccz .Lsel_m5
	s_branch .Lsel_exit

; __device__ __forceinline__ void select_item(const Frame& F, int l, int samp, int b, int c, int qg) {
;     ...
;             const unsigned candA = prefixA | (1u << bit), candB = prefixB | (1u << bit), cA1 = candA - 1u, cB1 = candB - 1u; unsigned a4[4] = {0u, 0u, 0u, 0u}, b4[4] = {0u, 0u, 0u, 0u};
; #pragma unroll
;             for (int j = 0; j < 64; ++j) { a4[j & 3] += min(__builtin_elementwise_sub_sat(keyA[j], cA1), 1u); b4[j & 3] += min(__builtin_elementwise_sub_sat(keyB[j], cB1), 1u); }
;             const int cntA = wave_sum_i_dpp((int)((a4[0] + a4[1]) + (a4[2] + a4[3]))), cntB = wave_sum_i_dpp((int)((b4[0] + b4[1]) + (b4[2] + b4[3])));
;             if (!doneA) { if (cntA >= 256) prefixA = candA; if (cntA == 256) doneA = true; }
;             if (!doneB) { if (cntB >= 256) prefixB = candB; if (cntB == 256) doneB = true; }
;         }
.Lsel_m7:
	s_mov_b64 s[6:7], s[0:1]
	s_lshl_b32 s0, 1, s11
	s_or_b32 s13, s0, s10
	s_or_b32 s12, s0, s33
	s_add_i32 s14, s13, -1
	s_add_i32 s15, s12, -1
	v_sub_co_u32_e64 v2, s[8:9], s11, 1
	s_nop 0
	v_readfirstlane_b32 s11, v2
	s_mov_b64 s[4:5], s[42:43]
	s_cmp_lt_u32 s14, 0x7fffff
	s_cselect_b32 s0, 8, 0
	v_mov_b32_e32 v2, s0
	s_cmp_lt_u32 s15, 0x7fffff
	s_cselect_b32 s0, 8, 0
	v_mov_b32_e32 v3, s0
	v_cmp_lt_u32_e64 s[0:1], s14, v127
	v_cmp_lt_u32_e64 s[100:101], s15, v81
	v_cmp_lt_u32_e32 vcc, s14, v4
	v_cndmask_b32_e64 v132, 0, 1, s[0:1]
	v_cndmask_b32_e64 v133, 0, 1, s[100:101]
	v_addc_co_u32_e32 v2, vcc, v2, v132, vcc
	v_cmp_lt_u32_e32 vcc, s15, v6
	v_cmp_lt_u32_e64 s[0:1], s14, v65
	v_cmp_lt_u32_e64 s[100:101], s15, v7
	v_addc_co_u32_e32 v3, vcc, v3, v133, vcc
	v_cmp_lt_u32_e32 vcc, s14, v129
	v_cndmask_b32_e64 v132, 0, 1, s[0:1]
	v_cndmask_b32_e64 v133, 0, 1, s[100:101]
	v_addc_co_u32_e32 v2, vcc, v2, v132, vcc
	v_cmp_lt_u32_e32 vcc, s15, v8
	v_cmp_lt_u32_e64 s[0:1], s14, v70
	v_cmp_lt_u32_e64 s[100:101], s15, v9
	v_addc_co_u32_e32 v3, vcc, v3, v133, vcc
	v_cmp_lt_u32_e32 vcc, s14, v67
	v_cndmask_b32_e64 v132, 0, 1, s[0:1]
	v_cndmask_b32_e64 v133, 0, 1, s[100:101]
	v_addc_co_u32_e32 v2, vcc, v2, v132, vcc
	v_cmp_lt_u32_e32 vcc, s15, v10
	v_cmp_lt_u32_e64 s[0:1], s14, v5
	v_cmp_lt_u32_e64 s[100:101], s15, v11
	v_addc_co_u32_e32 v3, vcc, v3, v133, vcc
	v_cmp_lt_u32_e32 vcc, s14, v69
	v_cndmask_b32_e64 v132, 0, 1, s[0:1]
	v_cndmask_b32_e64 v133, 0, 1, s[100:101]
	v_addc_co_u32_e32 v2, vcc, v2, v132, vcc
	v_cmp_lt_u32_e32 vcc, s15, v12
	v_cmp_lt_u32_e64 s[0:1], s14, v66
	v_cmp_lt_u32_e64 s[100:101], s15, v17
	v_addc_co_u32_e32 v3, vcc, v3, v133, vcc
	v_cmp_lt_u32_e32 vcc, s14, v71
	v_cndmask_b32_e64 v132, 0, 1, s[0:1]
	v_cndmask_b32_e64 v133, 0, 1, s[100:101]
	v_addc_co_u32_e32 v2, vcc, v2, v132, vcc
	v_cmp_lt_u32_e32 vcc, s15, v18
	v_cmp_lt_u32_e64 s[0:1], s14, v79
	v_cmp_lt_u32_e64 s[100:101], s15, v19
	v_addc_co_u32_e32 v3, vcc, v3, v133, vcc
	v_cmp_lt_u32_e32 vcc, s14, v72
	v_cndmask_b32_e64 v132, 0, 1, s[0:1]
	v_cndmask_b32_e64 v133, 0, 1, s[100:101]
	v_addc_co_u32_e32 v2, vcc, v2, v132, vcc
	v_cmp_lt_u32_e32 vcc, s15, v20
	v_cmp_lt_u32_e64 s[0:1], s14, v76
	v_cmp_lt_u32_e64 s[100:101], s15, v25
	v_addc_co_u32_e32 v3, vcc, v3, v133, vcc
	v_cmp_lt_u32_e32 vcc, s14, v74
	v_cndmask_b32_e64 v132, 0, 1, s[0:1]
	v_cndmask_b32_e64 v133, 0, 1, s[100:101]
	v_addc_co_u32_e32 v2, vcc, v2, v132, vcc
	v_cmp_lt_u32_e32 vcc, s15, v26
	v_cmp_lt_u32_e64 s[0:1], s14, v78
	v_cmp_lt_u32_e64 s[100:101], s15, v27
	v_addc_co_u32_e32 v3, vcc, v3, v133, vcc
	v_cmp_lt_u32_e32 vcc, s14, v92
	v_cndmask_b32_e64 v132, 0, 1, s[0:1]
	v_cndmask_b32_e64 v133, 0, 1, s[100:101]
	v_addc_co_u32_e32 v2, vcc, v2, v132, vcc
	v_cmp_lt_u32_e32 vcc, s15, v28
	v_cmp_lt_u32_e64 s[0:1], s14, v86
	v_cmp_lt_u32_e64 s[100:101], s15, v33
	v_addc_co_u32_e32 v3, vcc, v3, v133, vcc
	v_cmp_lt_u32_e32 vcc, s14, v89
	v_cndmask_b32_e64 v132, 0, 1, s[0:1]
	v_cndmask_b32_e64 v133, 0, 1, s[100:101]
	v_addc_co_u32_e32 v2, vcc, v2, v132, vcc
	v_cmp_lt_u32_e32 vcc, s15, v34
	v_cmp_lt_u32_e64 s[0:1], s14, v88
	v_cmp_lt_u32_e64 s[100:101], s15, v35
	v_addc_co_u32_e32 v3, vcc, v3, v133, vcc
	v_cmp_lt_u32_e32 vcc, s14, v91
	v_cndmask_b32_e64 v132, 0, 1, s[0:1]
	v_cndmask_b32_e64 v133, 0, 1, s[100:101]
	v_addc_co_u32_e32 v2, vcc, v2, v132, vcc
	v_cmp_lt_u32_e32 vcc, s15, v36
	v_cmp_lt_u32_e64 s[0:1], s14, v100
	v_cmp_lt_u32_e64 s[100:101], s15, v41
	v_addc_co_u32_e32 v3, vcc, v3, v133, vcc
	v_cmp_lt_u32_e32 vcc, s14, v94
	v_cndmask_b32_e64 v132, 0, 1, s[0:1]
	v_cndmask_b32_e64 v133, 0, 1, s[100:101]
	v_addc_co_u32_e32 v2, vcc, v2, v132, vcc
	v_cmp_lt_u32_e32 vcc, s15, v42
	v_cmp_lt_u32_e64 s[0:1], s14, v97
	v_cmp_lt_u32_e64 s[100:101], s15, v43
	v_addc_co_u32_e32 v3, vcc, v3, v133, vcc
	v_cmp_lt_u32_e32 vcc, s14, v96
	v_cndmask_b32_e64 v132, 0, 1, s[0:1]
	v_cndmask_b32_e64 v133, 0, 1, s[100:101]
	v_addc_co_u32_e32 v2, vcc, v2, v132, vcc
	v_cmp_lt_u32_e32 vcc, s15, v44
	v_cmp_lt_u32_e64 s[0:1], s14, v99
	v_cmp_lt_u32_e64 s[100:101], s15, v49
	v_addc_co_u32_e32 v3, vcc, v3, v133, vcc
	v_cmp_lt_u32_e32 vcc, s14, v108
	v_cndmask_b32_e64 v132, 0, 1, s[0:1]
	v_cndmask_b32_e64 v133, 0, 1, s[100:101]
	v_addc_co_u32_e32 v2, vcc, v2, v132, vcc
	v_cmp_lt_u32_e32 vcc, s15, v50
	v_cmp_lt_u32_e64 s[0:1], s14, v102
	v_cmp_lt_u32_e64 s[100:101], s15, v51
	v_addc_co_u32_e32 v3, vcc, v3, v133, vcc
	v_cmp_lt_u32_e32 vcc, s14, v105
	v_cndmask_b32_e64 v132, 0, 1, s[0:1]
	v_cndmask_b32_e64 v133, 0, 1, s[100:101]
	v_addc_co_u32_e32 v2, vcc, v2, v132, vcc
	v_cmp_lt_u32_e32 vcc, s15, v52
	v_cmp_lt_u32_e64 s[0:1], s14, v104
	v_cmp_lt_u32_e64 s[100:101], s15, v83
	v_addc_co_u32_e32 v3, vcc, v3, v133, vcc
	v_cmp_lt_u32_e32 vcc, s14, v107
	v_cndmask_b32_e64 v132, 0, 1, s[0:1]
	v_cndmask_b32_e64 v133, 0, 1, s[100:101]
	v_addc_co_u32_e32 v2, vcc, v2, v132, vcc
	v_cmp_lt_u32_e32 vcc, s15, v15
	v_cmp_lt_u32_e64 s[0:1], s14, v116
	v_cmp_lt_u32_e64 s[100:101], s15, v23
	v_addc_co_u32_e32 v3, vcc, v3, v133, vcc
	v_cmp_lt_u32_e32 vcc, s14, v110
	v_cndmask_b32_e64 v132, 0, 1, s[0:1]
	v_cndmask_b32_e64 v133, 0, 1, s[100:101]
	v_addc_co_u32_e32 v2, vcc, v2, v132, vcc
	v_cmp_lt_u32_e32 vcc, s15, v31
	v_cmp_lt_u32_e64 s[0:1], s14, v113
	v_cmp_lt_u32_e64 s[100:101], s15, v39
	v_addc_co_u32_e32 v3, vcc, v3, v133, vcc
	v_cmp_lt_u32_e32 vcc, s14, v112
	v_cndmask_b32_e64 v132, 0, 1, s[0:1]
; __device__ __forceinline__ void select_item(const Frame& F, int l, int samp, int b, int c, int qg) {
;     ...
;             const unsigned candA = prefixA | (1u << bit), candB = prefixB | (1u << bit), cA1 = candA - 1u, cB1 = candB - 1u; unsigned a4[4] = {0u, 0u, 0u, 0u}, b4[4] = {0u, 0u, 0u, 0u};
; #pragma unroll
;             for (int j = 0; j < 64; ++j) { a4[j & 3] += min(__builtin_elementwise_sub_sat(keyA[j], cA1), 1u); b4[j & 3] += min(__builtin_elementwise_sub_sat(keyB[j], cB1), 1u); }
;             const int cntA = wave_sum_i_dpp((int)((a4[0] + a4[1]) + (a4[2] + a4[3]))), cntB = wave_sum_i_dpp((int)((b4[0] + b4[1]) + (b4[2] + b4[3])));
;             if (!doneA) { if (cntA >= 256) prefixA = candA; if (cntA == 256) doneA = true; }
;             if (!doneB) { if (cntB >= 256) prefixB = candB; if (cntB == 256) doneB = true; }
;         }
	v_cndmask_b32_e64 v133, 0, 1, s[100:101]
	v_addc_co_u32_e32 v2, vcc, v2, v132, vcc
	v_cmp_lt_u32_e32 vcc, s15, v47
	v_cmp_lt_u32_e64 s[0:1], s14, v115
	v_cmp_lt_u32_e64 s[100:101], s15, v55
	v_addc_co_u32_e32 v3, vcc, v3, v133, vcc
	v_cmp_lt_u32_e32 vcc, s14, v128
	v_cndmask_b32_e64 v132, 0, 1, s[0:1]
	v_cndmask_b32_e64 v133, 0, 1, s[100:101]
	v_addc_co_u32_e32 v2, vcc, v2, v132, vcc
	v_cmp_lt_u32_e32 vcc, s15, v82
	v_cmp_lt_u32_e64 s[0:1], s14, v75
	v_cmp_lt_u32_e64 s[100:101], s15, v16
	v_addc_co_u32_e32 v3, vcc, v3, v133, vcc
	v_cmp_lt_u32_e32 vcc, s14, v87
	v_cndmask_b32_e64 v132, 0, 1, s[0:1]
	v_cndmask_b32_e64 v133, 0, 1, s[100:101]
	v_addc_co_u32_e32 v2, vcc, v2, v132, vcc
	v_cmp_lt_u32_e32 vcc, s15, v24
	v_cmp_lt_u32_e64 s[0:1], s14, v95
	v_cmp_lt_u32_e64 s[100:101], s15, v32
	v_addc_co_u32_e32 v3, vcc, v3, v133, vcc
	v_cmp_lt_u32_e32 vcc, s14, v103
	v_cndmask_b32_e64 v132, 0, 1, s[0:1]
	v_cndmask_b32_e64 v133, 0, 1, s[100:101]
	v_addc_co_u32_e32 v2, vcc, v2, v132, vcc
	v_cmp_lt_u32_e32 vcc, s15, v40
	v_cmp_lt_u32_e64 s[0:1], s14, v111
	v_cmp_lt_u32_e64 s[100:101], s15, v48
	v_addc_co_u32_e32 v3, vcc, v3, v133, vcc
	v_cmp_lt_u32_e32 vcc, s14, v119
	v_cndmask_b32_e64 v132, 0, 1, s[0:1]
	v_cndmask_b32_e64 v133, 0, 1, s[100:101]
	v_addc_co_u32_e32 v2, vcc, v2, v132, vcc
	v_cmp_lt_u32_e32 vcc, s15, v56
	v_cmp_lt_u32_e64 s[0:1], s14, v131
	v_cmp_lt_u32_e64 s[100:101], s15, v85
	v_addc_co_u32_e32 v3, vcc, v3, v133, vcc
	v_cmp_lt_u32_e32 vcc, s14, v68
	v_cndmask_b32_e64 v132, 0, 1, s[0:1]
	v_cndmask_b32_e64 v133, 0, 1, s[100:101]
	v_addc_co_u32_e32 v2, vcc, v2, v132, vcc
	v_cmp_lt_u32_e32 vcc, s15, v13
	v_cmp_lt_u32_e64 s[0:1], s14, v77
	v_cmp_lt_u32_e64 s[100:101], s15, v21
	v_addc_co_u32_e32 v3, vcc, v3, v133, vcc
	v_cmp_lt_u32_e32 vcc, s14, v90
	v_cndmask_b32_e64 v132, 0, 1, s[0:1]
	v_cndmask_b32_e64 v133, 0, 1, s[100:101]
	v_addc_co_u32_e32 v2, vcc, v2, v132, vcc
	v_cmp_lt_u32_e32 vcc, s15, v29
	v_cmp_lt_u32_e64 s[0:1], s14, v98
	v_cmp_lt_u32_e64 s[100:101], s15, v37
	v_addc_co_u32_e32 v3, vcc, v3, v133, vcc
	v_cmp_lt_u32_e32 vcc, s14, v106
	v_cndmask_b32_e64 v132, 0, 1, s[0:1]
	v_cndmask_b32_e64 v133, 0, 1, s[100:101]
	v_addc_co_u32_e32 v2, vcc, v2, v132, vcc
	v_cmp_lt_u32_e32 vcc, s15, v45
	v_cmp_lt_u32_e64 s[0:1], s14, v114
	v_cmp_lt_u32_e64 s[100:101], s15, v53
	v_addc_co_u32_e32 v3, vcc, v3, v133, vcc
	v_cmp_lt_u32_e32 vcc, s14, v130
	v_cndmask_b32_e64 v132, 0, 1, s[0:1]
	v_cndmask_b32_e64 v133, 0, 1, s[100:101]
	v_addc_co_u32_e32 v2, vcc, v2, v132, vcc
	v_cmp_lt_u32_e32 vcc, s15, v84
	v_cmp_lt_u32_e64 s[0:1], s14, v73
	v_cmp_lt_u32_e64 s[100:101], s15, v14
	v_addc_co_u32_e32 v3, vcc, v3, v133, vcc
	v_cmp_lt_u32_e32 vcc, s14, v80
	v_cndmask_b32_e64 v132, 0, 1, s[0:1]
	v_cndmask_b32_e64 v133, 0, 1, s[100:101]
	v_addc_co_u32_e32 v2, vcc, v2, v132, vcc
	v_cmp_lt_u32_e32 vcc, s15, v22
	v_cmp_lt_u32_e64 s[0:1], s14, v93
	v_cmp_lt_u32_e64 s[100:101], s15, v30
	v_addc_co_u32_e32 v3, vcc, v3, v133, vcc
	v_cmp_lt_u32_e32 vcc, s14, v101
	v_cndmask_b32_e64 v132, 0, 1, s[0:1]
	v_cndmask_b32_e64 v133, 0, 1, s[100:101]
	v_addc_co_u32_e32 v2, vcc, v2, v132, vcc
	v_cmp_lt_u32_e32 vcc, s15, v38
	v_cmp_lt_u32_e64 s[0:1], s14, v109
	v_cmp_lt_u32_e64 s[100:101], s15, v46
	v_addc_co_u32_e32 v3, vcc, v3, v133, vcc
	v_cmp_lt_u32_e32 vcc, s14, v117
	v_cndmask_b32_e64 v132, 0, 1, s[0:1]
	v_cndmask_b32_e64 v133, 0, 1, s[100:101]
	v_addc_co_u32_e32 v2, vcc, v2, v132, vcc
	v_cmp_lt_u32_e32 vcc, s15, v54
	s_nop 1
	v_addc_co_u32_e32 v3, vcc, v3, v133, vcc
	s_nop 1
	v_add_u32_dpp v2, v2, v2 quad_perm:[1,0,3,2] row_mask:0xf bank_mask:0xf bound_ctrl:1
	v_add_u32_dpp v3, v3, v3 quad_perm:[1,0,3,2] row_mask:0xf bank_mask:0xf bound_ctrl:1
	s_nop 0
	v_add_u32_dpp v2, v2, v2 quad_perm:[2,3,0,1] row_mask:0xf bank_mask:0xf bound_ctrl:1
	v_add_u32_dpp v3, v3, v3 quad_perm:[2,3,0,1] row_mask:0xf bank_mask:0xf bound_ctrl:1
	s_nop 0
	v_add_u32_dpp v2, v2, v2 row_half_mirror row_mask:0xf bank_mask:0xf bound_ctrl:1
	v_add_u32_dpp v3, v3, v3 row_half_mirror row_mask:0xf bank_mask:0xf bound_ctrl:1
	s_nop 0
	v_add_u32_dpp v2, v2, v2 row_mirror row_mask:0xf bank_mask:0xf bound_ctrl:1
	v_add_u32_dpp v3, v3, v3 row_mirror row_mask:0xf bank_mask:0xf bound_ctrl:1
	s_nop 0
	v_add_u32_dpp v2, v2, v2 row_bcast:15 row_mask:0xa bank_mask:0xf
	v_add_u32_dpp v3, v3, v3 row_bcast:15 row_mask:0xa bank_mask:0xf
	s_nop 0
	v_add_u32_dpp v2, v2, v2 row_bcast:31 row_mask:0xc bank_mask:0xf
	v_add_u32_dpp v3, v3, v3 row_bcast:31 row_mask:0xc bank_mask:0xf
	v_readlane_b32 s0, v2, 63
	s_cmpk_gt_i32 s0, 0xff
	s_cselect_b32 s13, s13, s10
	s_cmpk_eq_i32 s0, 0x100
	s_cselect_b64 s[0:1], -1, 0
	s_or_b64 s[0:1], s[6:7], s[0:1]
	s_and_b64 s[6:7], s[6:7], exec
	s_cselect_b32 s10, s10, s13
	v_readlane_b32 s14, v3, 63
	s_cmpk_gt_i32 s14, 0xff
	s_cselect_b32 s12, s12, s33
	s_cmpk_eq_i32 s14, 0x100
	s_cselect_b64 s[6:7], -1, 0
	s_or_b64 s[42:43], s[42:43], s[6:7]
	s_and_b64 s[4:5], s[4:5], exec
	s_cselect_b32 s33, s33, s12
	s_and_b64 s[4:5], s[0:1], s[42:43]
	s_or_b64 s[4:5], s[8:9], s[4:5]
	s_and_b64 vcc, exec, s[4:5]
	s_cbranch_vccz .Lsel_m7
	s_branch .Lsel_exit
.Lsel_disp:
	s_cmp_eq_u32 s98, 0
	s_cbranch_scc1 .Lsel_m1
	s_cmp_eq_u32 s98, 1
	s_cbranch_scc1 .Lsel_m2
	s_cmp_eq_u32 s98, 2
	s_cbranch_scc1 .Lsel_m3
	s_cmp_eq_u32 s98, 3
	s_cbranch_scc1 .Lsel_m4
	s_cmp_eq_u32 s98, 4
	s_cbranch_scc1 .Lsel_m5
	s_cmp_eq_u32 s98, 5
	s_cbranch_scc1 .Lsel_m6
	s_cmp_eq_u32 s98, 6
	s_cbranch_scc1 .Lsel_m7
